# PE work queue order permuted (96 GLA, 248 hyena, 168 GLA, 264 hyena, small) for a shorter end game
# baseline (speedup 1.0000x reference)
.LBB0_1353:
	s_or_b64 exec, exec, s[16:17]
	v_readlane_b32 s4, v251, 20
	s_waitcnt lgkmcnt(0)
	s_barrier
	v_mov_b32_e32 v2, s4
	ds_read_b32 v2, v2
	s_mov_b64 s[14:15], -1
	s_waitcnt lgkmcnt(0)
	v_add_u32_e32 v4, 0xa8, v2
	v_subrev_u32_e32 v5, 0xf8, v2
	v_cmp_gt_u32_e32 vcc, 0x158, v2
	s_nop 1
	v_cndmask_b32_e32 v4, v5, v4, vcc
	v_cmp_gt_u32_e32 vcc, 0x60, v2
	s_nop 1
	v_cndmask_b32_e32 v4, v4, v2, vcc
	v_cmp_gt_u32_e32 vcc, 0x200, v2
	s_nop 1
	v_cndmask_b32_e32 v2, v2, v4, vcc
	v_cmp_le_i32_e32 vcc, s29, v2
	v_readfirstlane_b32 s9, v2
	s_cbranch_vccnz .LBB0_1348
	s_cmpk_gt_i32 s9, 0x107
	s_cbranch_scc0 .LBB0_1549
	s_add_i32 s4, s9, 0xfffffef8
	s_and_b32 s5, s4, 0x100
	s_or_b32 s6, s5, 0x4000
	s_lshl_b32 s5, s4, 5
	s_and_b32 s12, s4, 0xff
	s_and_b32 s7, s5, 0x2000
	s_cmpk_lt_u32 s4, 0x200
	s_cselect_b64 s[18:19], -1, 0
	s_and_b64 s[4:5], s[18:19], exec
	s_movk_i32 s4, 0x2000
	s_cselect_b32 s52, s4, 0x100
	s_mul_i32 s4, s12, 0x8400
	v_mov_b32_e32 v59, v0
	v_writelane_b32 v251, s9, 58
	s_cselect_b32 s6, s7, s6
	s_lshl_b32 s4, s4, 1
	v_readlane_b32 s8, v252, 43
	v_readlane_b32 s9, v252, 44
	v_writelane_b32 v251, s4, 59
	s_add_u32 s7, s8, s4
	s_load_dwordx2 s[4:5], s[0:1], 0x98
	s_addc_u32 s8, s9, 0
	s_lshl_b32 s6, s6, 1
	v_writelane_b32 v251, s6, 60
	s_add_u32 s16, s7, s6
	v_readlane_b32 s10, v251, 39
	s_addc_u32 s17, s8, 0
	s_mul_i32 s6, s10, 0x4800
	s_waitcnt lgkmcnt(0)
	s_add_u32 s4, s4, s6
	s_load_dwordx2 s[6:7], s[0:1], 0xa0
	s_mul_hi_u32 s8, s10, 0x4800
	s_addc_u32 s5, s5, s8
	s_lshl_b32 s8, s12, 3
	s_add_u32 s44, s4, s8
	s_addc_u32 s45, s5, 0
	s_mul_i32 s4, s10, 0x1800
	s_waitcnt lgkmcnt(0)
	s_add_u32 s4, s6, s4
	s_mul_hi_u32 s5, s10, 0x1800
	v_mov_b32_e32 v2, s44
	s_addc_u32 s5, s7, s5
	v_add_co_u32_e32 v6, vcc, 0x1000, v2
	v_mov_b32_e32 v9, s45
	s_add_u32 s26, s4, s8
	v_addc_co_u32_e32 v7, vcc, 0, v9, vcc
	s_addc_u32 s27, s5, 0
	v_mov_b64_e32 v[4:5], s[44:45]
	v_add_co_u32_e32 v8, vcc, 0x3000, v2
	v_lshlrev_b32_e32 v52, 3, v59
	s_nop 0
	v_addc_co_u32_e32 v9, vcc, 0, v9, vcc
	flat_load_dword v89, v[4:5]
	flat_load_dword v83, v[6:7] offset:2048
	flat_load_dword v85, v[8:9]
	v_mov_b64_e32 v[4:5], s[26:27]
	flat_load_dword v87, v[4:5]
	v_cmp_gt_i32_e64 s[34:35], s52, v52
	v_mov_b32_e32 v64, 0
	v_mov_b32_e32 v43, 0
	v_ashrrev_i32_e32 v53, 31, v52
	v_mov_b32_e32 v42, 0
	v_mov_b32_e32 v41, 0
	v_mov_b32_e32 v40, 0
	v_mov_b32_e32 v65, 0
	v_readlane_b32 s11, v251, 40
	s_and_saveexec_b64 s[38:39], s[34:35]
	s_cbranch_execz .LBB0_1361
	v_lshl_add_u64 v[4:5], v[52:53], 1, s[16:17]
	global_load_dwordx4 v[40:43], v[4:5], off
	v_cmp_lt_i32_e32 vcc, 0, v52
	v_mov_b32_e32 v65, 0
	v_mov_b32_e32 v64, 0
	s_and_saveexec_b64 s[14:15], vcc
	s_cbranch_execz .LBB0_1358
	v_mov_b32_e32 v2, v52
	v_lshl_add_u64 v[6:7], v[2:3], 1, s[16:17]
	global_load_ushort v64, v[6:7], off offset:-2
